# L2 in-proj unit split rebalanced 9/7 (weight-converting group gets fewer GEMM units) + attn_sw epilogue batching/permlane
# baseline (speedup 1.0000x reference)
; template <int L>
; __device__ __forceinline__ void layer_body(const Ctx& c, const Args& args, const XcdBarrier& bar, int lo, int hi) {
;     ...
;             else if constexpr (L == 2) { pg8::ProbSplit S; S.init(XB, Wmi, 2048, 2048, 2048, 64, 32, c.G, cid); S.nA = NA; S.nB = NBU; pg8::EpiP<StBf16BiasGelu> E{{PROJ, 8192, args.in[19]}, RS}; pg8::gemm_phase(c.lds, S, E); }
.LBB0_3442:
	s_cmp_lg_u32 s26, 0
	s_cselect_b32 s26, 9, 0
	s_cselect_b32 s99, 5, 7
	s_lshl_b32 s6, s26, 7
	s_add_i32 s6, s27, s6
	s_cmpk_gt_i32 s6, 0x7ff
	v_readfirstlane_b32 s28, v0
	s_cbranch_scc1 .LBB0_3463
	s_ashr_i32 s7, s6, 31
	s_lshr_b32 s7, s7, 29
	s_add_i32 s10, s6, s7
	s_and_b32 s7, s10, -8
	s_sub_i32 s8, s6, s7
	s_cmp_gt_i32 s8, -1
	s_cbranch_scc0 .LBB0_3445
	s_lshl_b32 s9, s8, 8
	s_ashr_i32 s6, s10, 3
	s_cbranch_execz .LBB0_3446
	s_branch .LBB0_3447

; template <class PT, class Epi>
; __device__ __forceinline__ void gemm_phase_once(LAS unsigned char* lds, const PT& S, const Epi& E, bool epi_on) {
;     ...
;         const bool has_next = S.next(ui + 1, nxt);
.LBB0_3450:
	s_mov_b32 s9, s35
	s_add_i32 s35, s35, 1
	s_cmp_gt_u32 s9, s99
	s_mov_b64 s[24:25], 0
	s_cbranch_scc1 .LBB0_3457
	s_add_i32 s9, s35, s26
	s_lshl_b32 s9, s9, 7
	s_add_i32 s9, s9, s27
	s_cmpk_gt_i32 s9, 0x7ff
	s_cbranch_scc1 .LBB0_3457
	s_ashr_i32 s8, s9, 31
	s_lshr_b32 s8, s8, 29
	s_add_i32 s10, s9, s8
	s_and_b32 s8, s10, -8
	s_sub_i32 s11, s9, s8
	s_cmp_gt_i32 s11, -1
	s_mov_b64 s[8:9], -1
	s_cbranch_scc0 .LBB0_3454
	s_lshl_b32 s12, s11, 8
	s_mov_b64 s[8:9], 0
